# second input projection: output stores with sc1 (write-through, not kept in L2)
# speedup vs baseline: 1.0054x; 1.0016x over previous
.LBB0_501:
	v_lshl_add_u32 v156, s42, 8, v158
	s_cmp_eq_u32 s67, 0
	v_or_b32_e32 v168, 16, v156
	v_or_b32_e32 v167, 32, v156
	v_or_b32_e32 v166, 48, v156
	v_add_u32_e32 v165, 0x80, v156
	v_add_u32_e32 v164, 0x90, v156
	v_add_u32_e32 v163, 0xa0, v156
	v_add_u32_e32 v162, 0xb0, v156
	s_cbranch_scc1 .LBB0_503
	v_lshl_or_b32 v128, s50, 8, v160
	v_ashrrev_i32_e32 v129, 31, v128
	v_lshl_add_u64 v[132:133], v[128:129], 1, s[14:15]
	s_mov_b32 s26, 0x8100
	v_mad_i64_i32 v[134:135], s[4:5], v156, s26, v[132:133]
	v_cvt_pk_bf16_f32 v128, v124, v125
	v_cvt_pk_bf16_f32 v129, v126, v127
	v_cvt_pk_bf16_f32 v130, v120, v121
	v_cvt_pk_bf16_f32 v131, v122, v123
	global_store_dwordx4 v[134:135], v[128:131], off sc1
	s_mov_b32 s73, 0x8100
	s_nop 0
	v_cvt_pk_bf16_f32 v128, v116, v117
	v_cvt_pk_bf16_f32 v129, v118, v119
	v_cvt_pk_bf16_f32 v130, v112, v113
	v_cvt_pk_bf16_f32 v131, v114, v115
	global_store_dwordx4 v[134:135], v[128:131], off offset:256 sc1
	v_mad_i64_i32 v[134:135], s[4:5], v168, s26, v[132:133]
	s_nop 0
	v_cvt_pk_bf16_f32 v128, v108, v109
	v_cvt_pk_bf16_f32 v129, v110, v111
	v_cvt_pk_bf16_f32 v130, v104, v105
	v_cvt_pk_bf16_f32 v131, v106, v107
	global_store_dwordx4 v[134:135], v[128:131], off sc1
	s_nop 1
	v_cvt_pk_bf16_f32 v128, v100, v101
	v_cvt_pk_bf16_f32 v129, v102, v103
	v_cvt_pk_bf16_f32 v130, v96, v97
	v_cvt_pk_bf16_f32 v131, v98, v99
	global_store_dwordx4 v[134:135], v[128:131], off offset:256 sc1
	v_mad_i64_i32 v[134:135], s[4:5], v167, s26, v[132:133]
	s_nop 0
	v_cvt_pk_bf16_f32 v128, v92, v93
	v_cvt_pk_bf16_f32 v129, v94, v95
	v_cvt_pk_bf16_f32 v130, v88, v89
	v_cvt_pk_bf16_f32 v131, v90, v91
	global_store_dwordx4 v[134:135], v[128:131], off sc1
	s_nop 1
	v_cvt_pk_bf16_f32 v128, v84, v85
	v_cvt_pk_bf16_f32 v129, v86, v87
	v_cvt_pk_bf16_f32 v130, v80, v81
	v_cvt_pk_bf16_f32 v131, v82, v83
	global_store_dwordx4 v[134:135], v[128:131], off offset:256 sc1
	v_mad_i64_i32 v[134:135], s[4:5], v166, s26, v[132:133]
	s_nop 0
	v_cvt_pk_bf16_f32 v128, v76, v77
	v_cvt_pk_bf16_f32 v129, v78, v79
	v_cvt_pk_bf16_f32 v130, v72, v73
	v_cvt_pk_bf16_f32 v131, v74, v75
	global_store_dwordx4 v[134:135], v[128:131], off sc1
	s_nop 1
	v_cvt_pk_bf16_f32 v128, v68, v69
	v_cvt_pk_bf16_f32 v129, v70, v71
	v_cvt_pk_bf16_f32 v130, v64, v65
	v_cvt_pk_bf16_f32 v131, v66, v67
	global_store_dwordx4 v[134:135], v[128:131], off offset:256 sc1
	v_mad_i64_i32 v[134:135], s[4:5], v165, s26, v[132:133]
	s_nop 0
	v_cvt_pk_bf16_f32 v128, v60, v61
	v_cvt_pk_bf16_f32 v129, v62, v63
	v_cvt_pk_bf16_f32 v130, v56, v57
	v_cvt_pk_bf16_f32 v131, v58, v59
	global_store_dwordx4 v[134:135], v[128:131], off sc1
	s_nop 1
	v_cvt_pk_bf16_f32 v128, v52, v53
	v_cvt_pk_bf16_f32 v129, v54, v55
	v_cvt_pk_bf16_f32 v130, v48, v49
	v_cvt_pk_bf16_f32 v131, v50, v51
	global_store_dwordx4 v[134:135], v[128:131], off offset:256 sc1
	v_mad_i64_i32 v[134:135], s[4:5], v164, s26, v[132:133]
	s_nop 0
	v_cvt_pk_bf16_f32 v128, v44, v45
	v_cvt_pk_bf16_f32 v129, v46, v47
	v_cvt_pk_bf16_f32 v130, v40, v41
	v_cvt_pk_bf16_f32 v131, v42, v43
	global_store_dwordx4 v[134:135], v[128:131], off sc1
	s_nop 1
	v_cvt_pk_bf16_f32 v128, v36, v37
	v_cvt_pk_bf16_f32 v129, v38, v39
	v_cvt_pk_bf16_f32 v130, v32, v33
	v_cvt_pk_bf16_f32 v131, v34, v35
	global_store_dwordx4 v[134:135], v[128:131], off offset:256 sc1
	v_mad_i64_i32 v[134:135], s[4:5], v163, s26, v[132:133]
	s_nop 0
	v_cvt_pk_bf16_f32 v128, v28, v29
	v_cvt_pk_bf16_f32 v129, v30, v31
	v_cvt_pk_bf16_f32 v130, v24, v25
	v_cvt_pk_bf16_f32 v131, v26, v27
	global_store_dwordx4 v[134:135], v[128:131], off sc1
	s_nop 1
	v_cvt_pk_bf16_f32 v128, v20, v21
	v_cvt_pk_bf16_f32 v129, v22, v23
	v_cvt_pk_bf16_f32 v130, v16, v17
	v_cvt_pk_bf16_f32 v131, v18, v19
	global_store_dwordx4 v[134:135], v[128:131], off offset:256 sc1
	s_nop 1
	v_mad_i64_i32 v[128:129], s[4:5], v162, s26, v[132:133]
	v_cvt_pk_bf16_f32 v130, v12, v13
	v_cvt_pk_bf16_f32 v131, v14, v15
	v_cvt_pk_bf16_f32 v132, v8, v9
	v_cvt_pk_bf16_f32 v133, v10, v11
	global_store_dwordx4 v[128:129], v[130:133], off sc1
	s_cbranch_execz .LBB0_504
	s_branch .LBB0_568

.Linb_noscale:
	s_cmp_lt_i32 s50, 8
	s_cselect_b64 s[4:5], -1, 0
	s_movk_i32 s26, 0x880
	s_cselect_b32 s26, s26, 0x800
	s_cselect_b32 s42, s97, s61
	s_cselect_b32 s43, s60, s62
	s_cselect_b32 s27, 0, -8
	s_and_b64 s[4:5], s[4:5], s[28:29]
	s_add_i32 s27, s27, s50
	v_lshl_or_b32 v128, s27, 8, v160
	v_mad_u32_u24 v128, v156, s26, v128
	v_lshlrev_b32_e32 v128, 1, v128
	s_lshl_b32 s73, s26, 5
	s_and_b64 vcc, exec, s[4:5]
	s_cbranch_vccnz .Linb_rope
	v_cvt_pk_bf16_f32 v124, v124, v125
	v_cvt_pk_bf16_f32 v125, v126, v127
	v_cvt_pk_bf16_f32 v126, v120, v121
	v_cvt_pk_bf16_f32 v127, v122, v123
	global_store_dwordx4 v128, v[124:127], s[42:43] offset:0 sc1
	v_cvt_pk_bf16_f32 v116, v116, v117
	v_cvt_pk_bf16_f32 v117, v118, v119
	v_cvt_pk_bf16_f32 v118, v112, v113
	v_cvt_pk_bf16_f32 v119, v114, v115
	global_store_dwordx4 v128, v[116:119], s[42:43] offset:256 sc1
	s_mul_i32 s4, s73, 1
	v_add_u32_e32 v132, s4, v128
	v_cvt_pk_bf16_f32 v108, v108, v109
	v_cvt_pk_bf16_f32 v109, v110, v111
	v_cvt_pk_bf16_f32 v110, v104, v105
	v_cvt_pk_bf16_f32 v111, v106, v107
	global_store_dwordx4 v132, v[108:111], s[42:43] offset:0 sc1
	v_cvt_pk_bf16_f32 v100, v100, v101
	v_cvt_pk_bf16_f32 v101, v102, v103
	v_cvt_pk_bf16_f32 v102, v96, v97
	v_cvt_pk_bf16_f32 v103, v98, v99
	global_store_dwordx4 v132, v[100:103], s[42:43] offset:256 sc1
	s_mul_i32 s4, s73, 2
	v_add_u32_e32 v132, s4, v128
	v_cvt_pk_bf16_f32 v92, v92, v93
	v_cvt_pk_bf16_f32 v93, v94, v95
	v_cvt_pk_bf16_f32 v94, v88, v89
	v_cvt_pk_bf16_f32 v95, v90, v91
	global_store_dwordx4 v132, v[92:95], s[42:43] offset:0 sc1
	v_cvt_pk_bf16_f32 v84, v84, v85
	v_cvt_pk_bf16_f32 v85, v86, v87
	v_cvt_pk_bf16_f32 v86, v80, v81
	v_cvt_pk_bf16_f32 v87, v82, v83
	global_store_dwordx4 v132, v[84:87], s[42:43] offset:256 sc1
	s_mul_i32 s4, s73, 3
	v_add_u32_e32 v132, s4, v128
	v_cvt_pk_bf16_f32 v76, v76, v77
	v_cvt_pk_bf16_f32 v77, v78, v79
	v_cvt_pk_bf16_f32 v78, v72, v73
	v_cvt_pk_bf16_f32 v79, v74, v75
	global_store_dwordx4 v132, v[76:79], s[42:43] offset:0 sc1
	v_cvt_pk_bf16_f32 v68, v68, v69
	v_cvt_pk_bf16_f32 v69, v70, v71
	v_cvt_pk_bf16_f32 v70, v64, v65
	v_cvt_pk_bf16_f32 v71, v66, v67
	global_store_dwordx4 v132, v[68:71], s[42:43] offset:256 sc1
	s_mul_i32 s4, s73, 8
	v_add_u32_e32 v132, s4, v128
	v_cvt_pk_bf16_f32 v60, v60, v61
	v_cvt_pk_bf16_f32 v61, v62, v63
	v_cvt_pk_bf16_f32 v62, v56, v57
	v_cvt_pk_bf16_f32 v63, v58, v59
	global_store_dwordx4 v132, v[60:63], s[42:43] offset:0 sc1
	v_cvt_pk_bf16_f32 v52, v52, v53
	v_cvt_pk_bf16_f32 v53, v54, v55
	v_cvt_pk_bf16_f32 v54, v48, v49
	v_cvt_pk_bf16_f32 v55, v50, v51
	global_store_dwordx4 v132, v[52:55], s[42:43] offset:256 sc1
	s_mul_i32 s4, s73, 9
	v_add_u32_e32 v132, s4, v128
	v_cvt_pk_bf16_f32 v44, v44, v45
	v_cvt_pk_bf16_f32 v45, v46, v47
	v_cvt_pk_bf16_f32 v46, v40, v41
	v_cvt_pk_bf16_f32 v47, v42, v43
	global_store_dwordx4 v132, v[44:47], s[42:43] offset:0 sc1
	v_cvt_pk_bf16_f32 v36, v36, v37
	v_cvt_pk_bf16_f32 v37, v38, v39
	v_cvt_pk_bf16_f32 v38, v32, v33
	v_cvt_pk_bf16_f32 v39, v34, v35
	global_store_dwordx4 v132, v[36:39], s[42:43] offset:256 sc1
	s_mul_i32 s4, s73, 10
	v_add_u32_e32 v132, s4, v128
	v_cvt_pk_bf16_f32 v28, v28, v29
	v_cvt_pk_bf16_f32 v29, v30, v31
	v_cvt_pk_bf16_f32 v30, v24, v25
	v_cvt_pk_bf16_f32 v31, v26, v27
	global_store_dwordx4 v132, v[28:31], s[42:43] offset:0 sc1
	v_cvt_pk_bf16_f32 v20, v20, v21
	v_cvt_pk_bf16_f32 v21, v22, v23
	v_cvt_pk_bf16_f32 v22, v16, v17
	v_cvt_pk_bf16_f32 v23, v18, v19
	global_store_dwordx4 v132, v[20:23], s[42:43] offset:256 sc1
	s_mul_i32 s4, s73, 11
	v_add_u32_e32 v132, s4, v128
	v_cvt_pk_bf16_f32 v12, v12, v13
	v_cvt_pk_bf16_f32 v13, v14, v15
	v_cvt_pk_bf16_f32 v14, v8, v9
	v_cvt_pk_bf16_f32 v15, v10, v11
	global_store_dwordx4 v132, v[12:15], s[42:43] offset:0 sc1
	v_cvt_pk_bf16_f32 v4, v4, v5
	v_cvt_pk_bf16_f32 v5, v6, v7
	v_cvt_pk_bf16_f32 v6, v0, v1
	v_cvt_pk_bf16_f32 v7, v2, v3
	global_store_dwordx4 v132, v[4:7], s[42:43] offset:256 sc1
	s_branch .Linb_done
.Linb_rope:
	v_lshlrev_b32_e32 v129, 5, v156
	v_and_b32_e32 v129, 0xffe0, v129
	v_mov_b32_e32 v133, 0x80000000
	v_cndmask_b32_e64 v130, 0, v133, s[38:39]
	v_and_b32_e32 v133, 64, v240
	v_xor_b32_e32 v132, 16, v240
	v_add_u32_e32 v133, 64, v133
	v_cmp_lt_i32_e32 vcc, v132, v133
	s_nop 1
	v_cndmask_b32_e32 v132, v240, v132, vcc
	v_lshlrev_b32_e32 v131, 2, v132
	global_load_dwordx4 v[148:151], v129, s[10:11] offset:0
	global_load_dwordx4 v[152:155], v129, s[10:11] offset:16
	global_load_dwordx4 v[164:167], v129, s[12:13] offset:0
	global_load_dwordx4 v[168:171], v129, s[12:13] offset:16
	global_load_dwordx4 v[172:175], v129, s[10:11] offset:512
	global_load_dwordx4 v[176:179], v129, s[10:11] offset:528
	global_load_dwordx4 v[180:183], v129, s[12:13] offset:512
	global_load_dwordx4 v[184:187], v129, s[12:13] offset:528
	global_load_dwordx4 v[188:191], v129, s[10:11] offset:1024
	global_load_dwordx4 v[208:211], v129, s[10:11] offset:1040
	global_load_dwordx4 v[212:215], v129, s[12:13] offset:1024
	global_load_dwordx4 v[216:219], v129, s[12:13] offset:1040
	global_load_dwordx4 v[220:223], v129, s[10:11] offset:1536
	global_load_dwordx4 v[224:227], v129, s[10:11] offset:1552
	global_load_dwordx4 v[228:231], v129, s[12:13] offset:1536
	global_load_dwordx4 v[232:235], v129, s[12:13] offset:1552
	ds_bpermute_b32 v134, v131, v124
	ds_bpermute_b32 v135, v131, v125
	ds_bpermute_b32 v146, v131, v126
	ds_bpermute_b32 v147, v131, v127
	ds_bpermute_b32 v156, v131, v120
	ds_bpermute_b32 v157, v131, v121
	ds_bpermute_b32 v162, v131, v122
	ds_bpermute_b32 v163, v131, v123
	s_waitcnt vmcnt(12)
	v_cndmask_b32_e64 v148, v148, 1.0, s[40:41]
	v_cndmask_b32_e64 v149, v149, 1.0, s[40:41]
	v_cndmask_b32_e64 v150, v150, 1.0, s[40:41]
	v_cndmask_b32_e64 v151, v151, 1.0, s[40:41]
	v_cndmask_b32_e64 v152, v152, 1.0, s[40:41]
	v_cndmask_b32_e64 v153, v153, 1.0, s[40:41]
	v_cndmask_b32_e64 v154, v154, 1.0, s[40:41]
	v_cndmask_b32_e64 v155, v155, 1.0, s[40:41]
	v_xor_b32_e32 v164, v130, v164
	v_cndmask_b32_e64 v164, v164, 0, s[40:41]
	v_xor_b32_e32 v165, v130, v165
	v_cndmask_b32_e64 v165, v165, 0, s[40:41]
	v_xor_b32_e32 v166, v130, v166
	v_cndmask_b32_e64 v166, v166, 0, s[40:41]
	v_xor_b32_e32 v167, v130, v167
	v_cndmask_b32_e64 v167, v167, 0, s[40:41]
	v_xor_b32_e32 v168, v130, v168
	v_cndmask_b32_e64 v168, v168, 0, s[40:41]
	v_xor_b32_e32 v169, v130, v169
	v_cndmask_b32_e64 v169, v169, 0, s[40:41]
	v_xor_b32_e32 v170, v130, v170
	v_cndmask_b32_e64 v170, v170, 0, s[40:41]
	v_xor_b32_e32 v171, v130, v171
	v_cndmask_b32_e64 v171, v171, 0, s[40:41]
	s_waitcnt lgkmcnt(0)
	v_mul_f32_e32 v134, v164, v134
	v_mul_f32_e32 v135, v165, v135
	v_mul_f32_e32 v146, v166, v146
	v_mul_f32_e32 v147, v167, v147
	v_mul_f32_e32 v156, v168, v156
	v_mul_f32_e32 v157, v169, v157
	v_mul_f32_e32 v162, v170, v162
	v_mul_f32_e32 v163, v171, v163
	v_fma_f32 v124, v124, v148, v134
	v_fma_f32 v125, v125, v149, v135
	v_fma_f32 v126, v126, v150, v146
	v_fma_f32 v127, v127, v151, v147
	v_fma_f32 v120, v120, v152, v156
	v_fma_f32 v121, v121, v153, v157
	v_fma_f32 v122, v122, v154, v162
	v_fma_f32 v123, v123, v155, v163
	ds_bpermute_b32 v134, v131, v116
	ds_bpermute_b32 v135, v131, v117
	ds_bpermute_b32 v146, v131, v118
	ds_bpermute_b32 v147, v131, v119
	ds_bpermute_b32 v156, v131, v112
	ds_bpermute_b32 v157, v131, v113
	ds_bpermute_b32 v162, v131, v114
	ds_bpermute_b32 v163, v131, v115
	v_cvt_pk_bf16_f32 v124, v124, v125
	v_cvt_pk_bf16_f32 v125, v126, v127
	v_cvt_pk_bf16_f32 v126, v120, v121
	v_cvt_pk_bf16_f32 v127, v122, v123
	global_store_dwordx4 v128, v[124:127], s[42:43] offset:0 sc1
	s_waitcnt lgkmcnt(0)
	v_mul_f32_e32 v134, v164, v134
	v_mul_f32_e32 v135, v165, v135
	v_mul_f32_e32 v146, v166, v146
	v_mul_f32_e32 v147, v167, v147
	v_mul_f32_e32 v156, v168, v156
	v_mul_f32_e32 v157, v169, v157
	v_mul_f32_e32 v162, v170, v162
	v_mul_f32_e32 v163, v171, v163
	v_fma_f32 v116, v116, v148, v134
	v_fma_f32 v117, v117, v149, v135
	v_fma_f32 v118, v118, v150, v146
	v_fma_f32 v119, v119, v151, v147
	v_fma_f32 v112, v112, v152, v156
	v_fma_f32 v113, v113, v153, v157
	v_fma_f32 v114, v114, v154, v162
	v_fma_f32 v115, v115, v155, v163
	v_cvt_pk_bf16_f32 v116, v116, v117
	v_cvt_pk_bf16_f32 v117, v118, v119
	v_cvt_pk_bf16_f32 v118, v112, v113
	v_cvt_pk_bf16_f32 v119, v114, v115
	global_store_dwordx4 v128, v[116:119], s[42:43] offset:256 sc1
	ds_bpermute_b32 v134, v131, v108
	ds_bpermute_b32 v135, v131, v109
	ds_bpermute_b32 v146, v131, v110
	ds_bpermute_b32 v147, v131, v111
	ds_bpermute_b32 v156, v131, v104
	ds_bpermute_b32 v157, v131, v105
	ds_bpermute_b32 v162, v131, v106
	ds_bpermute_b32 v163, v131, v107
	s_waitcnt vmcnt(10)
	v_cndmask_b32_e64 v172, v172, 1.0, s[40:41]
	v_cndmask_b32_e64 v173, v173, 1.0, s[40:41]
	v_cndmask_b32_e64 v174, v174, 1.0, s[40:41]
	v_cndmask_b32_e64 v175, v175, 1.0, s[40:41]
	v_cndmask_b32_e64 v176, v176, 1.0, s[40:41]
	v_cndmask_b32_e64 v177, v177, 1.0, s[40:41]
	v_cndmask_b32_e64 v178, v178, 1.0, s[40:41]
	v_cndmask_b32_e64 v179, v179, 1.0, s[40:41]
	v_xor_b32_e32 v180, v130, v180
	v_cndmask_b32_e64 v180, v180, 0, s[40:41]
	v_xor_b32_e32 v181, v130, v181
	v_cndmask_b32_e64 v181, v181, 0, s[40:41]
	v_xor_b32_e32 v182, v130, v182
	v_cndmask_b32_e64 v182, v182, 0, s[40:41]
	v_xor_b32_e32 v183, v130, v183
	v_cndmask_b32_e64 v183, v183, 0, s[40:41]
	v_xor_b32_e32 v184, v130, v184
	v_cndmask_b32_e64 v184, v184, 0, s[40:41]
	v_xor_b32_e32 v185, v130, v185
	v_cndmask_b32_e64 v185, v185, 0, s[40:41]
	v_xor_b32_e32 v186, v130, v186
	v_cndmask_b32_e64 v186, v186, 0, s[40:41]
	v_xor_b32_e32 v187, v130, v187
	v_cndmask_b32_e64 v187, v187, 0, s[40:41]
	s_mul_i32 s4, s73, 1
	v_add_u32_e32 v132, s4, v128
	s_waitcnt lgkmcnt(0)
	v_mul_f32_e32 v134, v180, v134
	v_mul_f32_e32 v135, v181, v135
	v_mul_f32_e32 v146, v182, v146
	v_mul_f32_e32 v147, v183, v147
	v_mul_f32_e32 v156, v184, v156
	v_mul_f32_e32 v157, v185, v157
	v_mul_f32_e32 v162, v186, v162
	v_mul_f32_e32 v163, v187, v163
	v_fma_f32 v108, v108, v172, v134
	v_fma_f32 v109, v109, v173, v135
	v_fma_f32 v110, v110, v174, v146
	v_fma_f32 v111, v111, v175, v147
	v_fma_f32 v104, v104, v176, v156
	v_fma_f32 v105, v105, v177, v157
	v_fma_f32 v106, v106, v178, v162
	v_fma_f32 v107, v107, v179, v163
	ds_bpermute_b32 v134, v131, v100
	ds_bpermute_b32 v135, v131, v101
	ds_bpermute_b32 v146, v131, v102
	ds_bpermute_b32 v147, v131, v103
	ds_bpermute_b32 v156, v131, v96
	ds_bpermute_b32 v157, v131, v97
	ds_bpermute_b32 v162, v131, v98
	ds_bpermute_b32 v163, v131, v99
	v_cvt_pk_bf16_f32 v108, v108, v109
	v_cvt_pk_bf16_f32 v109, v110, v111
	v_cvt_pk_bf16_f32 v110, v104, v105
	v_cvt_pk_bf16_f32 v111, v106, v107
	global_store_dwordx4 v132, v[108:111], s[42:43] offset:0 sc1
	s_waitcnt lgkmcnt(0)
	v_mul_f32_e32 v134, v180, v134
	v_mul_f32_e32 v135, v181, v135
	v_mul_f32_e32 v146, v182, v146
	v_mul_f32_e32 v147, v183, v147
	v_mul_f32_e32 v156, v184, v156
	v_mul_f32_e32 v157, v185, v157
	v_mul_f32_e32 v162, v186, v162
	v_mul_f32_e32 v163, v187, v163
	v_fma_f32 v100, v100, v172, v134
	v_fma_f32 v101, v101, v173, v135
	v_fma_f32 v102, v102, v174, v146
	v_fma_f32 v103, v103, v175, v147
	v_fma_f32 v96, v96, v176, v156
	v_fma_f32 v97, v97, v177, v157
	v_fma_f32 v98, v98, v178, v162
	v_fma_f32 v99, v99, v179, v163
	v_cvt_pk_bf16_f32 v100, v100, v101
	v_cvt_pk_bf16_f32 v101, v102, v103
	v_cvt_pk_bf16_f32 v102, v96, v97
	v_cvt_pk_bf16_f32 v103, v98, v99
	global_store_dwordx4 v132, v[100:103], s[42:43] offset:256 sc1
	ds_bpermute_b32 v134, v131, v92
	ds_bpermute_b32 v135, v131, v93
	ds_bpermute_b32 v146, v131, v94
	ds_bpermute_b32 v147, v131, v95
	ds_bpermute_b32 v156, v131, v88
	ds_bpermute_b32 v157, v131, v89
	ds_bpermute_b32 v162, v131, v90
	ds_bpermute_b32 v163, v131, v91
	s_waitcnt vmcnt(8)
	v_cndmask_b32_e64 v188, v188, 1.0, s[40:41]
	v_cndmask_b32_e64 v189, v189, 1.0, s[40:41]
	v_cndmask_b32_e64 v190, v190, 1.0, s[40:41]
	v_cndmask_b32_e64 v191, v191, 1.0, s[40:41]
	v_cndmask_b32_e64 v208, v208, 1.0, s[40:41]
	v_cndmask_b32_e64 v209, v209, 1.0, s[40:41]
	v_cndmask_b32_e64 v210, v210, 1.0, s[40:41]
	v_cndmask_b32_e64 v211, v211, 1.0, s[40:41]
	v_xor_b32_e32 v212, v130, v212
	v_cndmask_b32_e64 v212, v212, 0, s[40:41]
	v_xor_b32_e32 v213, v130, v213
	v_cndmask_b32_e64 v213, v213, 0, s[40:41]
	v_xor_b32_e32 v214, v130, v214
	v_cndmask_b32_e64 v214, v214, 0, s[40:41]
	v_xor_b32_e32 v215, v130, v215
	v_cndmask_b32_e64 v215, v215, 0, s[40:41]
	v_xor_b32_e32 v216, v130, v216
	v_cndmask_b32_e64 v216, v216, 0, s[40:41]
	v_xor_b32_e32 v217, v130, v217
	v_cndmask_b32_e64 v217, v217, 0, s[40:41]
	v_xor_b32_e32 v218, v130, v218
	v_cndmask_b32_e64 v218, v218, 0, s[40:41]
	v_xor_b32_e32 v219, v130, v219
	v_cndmask_b32_e64 v219, v219, 0, s[40:41]
	s_mul_i32 s4, s73, 2
	v_add_u32_e32 v132, s4, v128
	s_waitcnt lgkmcnt(0)
	v_mul_f32_e32 v134, v212, v134
	v_mul_f32_e32 v135, v213, v135
	v_mul_f32_e32 v146, v214, v146
	v_mul_f32_e32 v147, v215, v147
	v_mul_f32_e32 v156, v216, v156
	v_mul_f32_e32 v157, v217, v157
	v_mul_f32_e32 v162, v218, v162
	v_mul_f32_e32 v163, v219, v163
	v_fma_f32 v92, v92, v188, v134
	v_fma_f32 v93, v93, v189, v135
	v_fma_f32 v94, v94, v190, v146
	v_fma_f32 v95, v95, v191, v147
	v_fma_f32 v88, v88, v208, v156
	v_fma_f32 v89, v89, v209, v157
	v_fma_f32 v90, v90, v210, v162
	v_fma_f32 v91, v91, v211, v163
	ds_bpermute_b32 v134, v131, v84
	ds_bpermute_b32 v135, v131, v85
	ds_bpermute_b32 v146, v131, v86
	ds_bpermute_b32 v147, v131, v87
	ds_bpermute_b32 v156, v131, v80
	ds_bpermute_b32 v157, v131, v81
	ds_bpermute_b32 v162, v131, v82
	ds_bpermute_b32 v163, v131, v83
	v_cvt_pk_bf16_f32 v92, v92, v93
	v_cvt_pk_bf16_f32 v93, v94, v95
	v_cvt_pk_bf16_f32 v94, v88, v89
	v_cvt_pk_bf16_f32 v95, v90, v91
	global_store_dwordx4 v132, v[92:95], s[42:43] offset:0 sc1
	s_waitcnt lgkmcnt(0)
	v_mul_f32_e32 v134, v212, v134
	v_mul_f32_e32 v135, v213, v135
	v_mul_f32_e32 v146, v214, v146
	v_mul_f32_e32 v147, v215, v147
	v_mul_f32_e32 v156, v216, v156
	v_mul_f32_e32 v157, v217, v157
	v_mul_f32_e32 v162, v218, v162
	v_mul_f32_e32 v163, v219, v163
	v_fma_f32 v84, v84, v188, v134
	v_fma_f32 v85, v85, v189, v135
	v_fma_f32 v86, v86, v190, v146
	v_fma_f32 v87, v87, v191, v147
	v_fma_f32 v80, v80, v208, v156
	v_fma_f32 v81, v81, v209, v157
	v_fma_f32 v82, v82, v210, v162
	v_fma_f32 v83, v83, v211, v163
	v_cvt_pk_bf16_f32 v84, v84, v85
	v_cvt_pk_bf16_f32 v85, v86, v87
	v_cvt_pk_bf16_f32 v86, v80, v81
	v_cvt_pk_bf16_f32 v87, v82, v83
	global_store_dwordx4 v132, v[84:87], s[42:43] offset:256 sc1
	ds_bpermute_b32 v134, v131, v76
	ds_bpermute_b32 v135, v131, v77
	ds_bpermute_b32 v146, v131, v78
	ds_bpermute_b32 v147, v131, v79
	ds_bpermute_b32 v156, v131, v72
	ds_bpermute_b32 v157, v131, v73
	ds_bpermute_b32 v162, v131, v74
	ds_bpermute_b32 v163, v131, v75
	s_waitcnt vmcnt(6)
	v_cndmask_b32_e64 v220, v220, 1.0, s[40:41]
	v_cndmask_b32_e64 v221, v221, 1.0, s[40:41]
	v_cndmask_b32_e64 v222, v222, 1.0, s[40:41]
	v_cndmask_b32_e64 v223, v223, 1.0, s[40:41]
	v_cndmask_b32_e64 v224, v224, 1.0, s[40:41]
	v_cndmask_b32_e64 v225, v225, 1.0, s[40:41]
	v_cndmask_b32_e64 v226, v226, 1.0, s[40:41]
	v_cndmask_b32_e64 v227, v227, 1.0, s[40:41]
	v_xor_b32_e32 v228, v130, v228
	v_cndmask_b32_e64 v228, v228, 0, s[40:41]
	v_xor_b32_e32 v229, v130, v229
	v_cndmask_b32_e64 v229, v229, 0, s[40:41]
	v_xor_b32_e32 v230, v130, v230
	v_cndmask_b32_e64 v230, v230, 0, s[40:41]
	v_xor_b32_e32 v231, v130, v231
	v_cndmask_b32_e64 v231, v231, 0, s[40:41]
	v_xor_b32_e32 v232, v130, v232
	v_cndmask_b32_e64 v232, v232, 0, s[40:41]
	v_xor_b32_e32 v233, v130, v233
	v_cndmask_b32_e64 v233, v233, 0, s[40:41]
	v_xor_b32_e32 v234, v130, v234
	v_cndmask_b32_e64 v234, v234, 0, s[40:41]
	v_xor_b32_e32 v235, v130, v235
	v_cndmask_b32_e64 v235, v235, 0, s[40:41]
	s_mul_i32 s4, s73, 3
	v_add_u32_e32 v132, s4, v128
	s_waitcnt lgkmcnt(0)
	v_mul_f32_e32 v134, v228, v134
	v_mul_f32_e32 v135, v229, v135
	v_mul_f32_e32 v146, v230, v146
	v_mul_f32_e32 v147, v231, v147
	v_mul_f32_e32 v156, v232, v156
	v_mul_f32_e32 v157, v233, v157
	v_mul_f32_e32 v162, v234, v162
	v_mul_f32_e32 v163, v235, v163
	v_fma_f32 v76, v76, v220, v134
	v_fma_f32 v77, v77, v221, v135
	v_fma_f32 v78, v78, v222, v146
	v_fma_f32 v79, v79, v223, v147
	v_fma_f32 v72, v72, v224, v156
	v_fma_f32 v73, v73, v225, v157
	v_fma_f32 v74, v74, v226, v162
	v_fma_f32 v75, v75, v227, v163
	ds_bpermute_b32 v134, v131, v68
	ds_bpermute_b32 v135, v131, v69
	ds_bpermute_b32 v146, v131, v70
	ds_bpermute_b32 v147, v131, v71
	ds_bpermute_b32 v156, v131, v64
	ds_bpermute_b32 v157, v131, v65
	ds_bpermute_b32 v162, v131, v66
	ds_bpermute_b32 v163, v131, v67
	v_cvt_pk_bf16_f32 v76, v76, v77
	v_cvt_pk_bf16_f32 v77, v78, v79
	v_cvt_pk_bf16_f32 v78, v72, v73
	v_cvt_pk_bf16_f32 v79, v74, v75
	global_store_dwordx4 v132, v[76:79], s[42:43] offset:0 sc1
	s_waitcnt lgkmcnt(0)
	v_mul_f32_e32 v134, v228, v134
	v_mul_f32_e32 v135, v229, v135
	v_mul_f32_e32 v146, v230, v146
	v_mul_f32_e32 v147, v231, v147
	v_mul_f32_e32 v156, v232, v156
	v_mul_f32_e32 v157, v233, v157
	v_mul_f32_e32 v162, v234, v162
	v_mul_f32_e32 v163, v235, v163
	v_fma_f32 v68, v68, v220, v134
	v_fma_f32 v69, v69, v221, v135
	v_fma_f32 v70, v70, v222, v146
	v_fma_f32 v71, v71, v223, v147
	v_fma_f32 v64, v64, v224, v156
	v_fma_f32 v65, v65, v225, v157
	v_fma_f32 v66, v66, v226, v162
	v_fma_f32 v67, v67, v227, v163
	v_cvt_pk_bf16_f32 v68, v68, v69
	v_cvt_pk_bf16_f32 v69, v70, v71
	v_cvt_pk_bf16_f32 v70, v64, v65
	v_cvt_pk_bf16_f32 v71, v66, v67
	global_store_dwordx4 v132, v[68:71], s[42:43] offset:256 sc1
	v_add_u32_e32 v133, 0x1000, v129
	global_load_dwordx4 v[148:151], v133, s[10:11] offset:0
	global_load_dwordx4 v[152:155], v133, s[10:11] offset:16
	global_load_dwordx4 v[164:167], v133, s[12:13] offset:0
	global_load_dwordx4 v[168:171], v133, s[12:13] offset:16
	global_load_dwordx4 v[172:175], v133, s[10:11] offset:512
	global_load_dwordx4 v[176:179], v133, s[10:11] offset:528
	global_load_dwordx4 v[180:183], v133, s[12:13] offset:512
	global_load_dwordx4 v[184:187], v133, s[12:13] offset:528
	global_load_dwordx4 v[188:191], v133, s[10:11] offset:1024
	global_load_dwordx4 v[208:211], v133, s[10:11] offset:1040
	global_load_dwordx4 v[212:215], v133, s[12:13] offset:1024
	global_load_dwordx4 v[216:219], v133, s[12:13] offset:1040
	global_load_dwordx4 v[220:223], v133, s[10:11] offset:1536
	global_load_dwordx4 v[224:227], v133, s[10:11] offset:1552
	global_load_dwordx4 v[228:231], v133, s[12:13] offset:1536
	global_load_dwordx4 v[232:235], v133, s[12:13] offset:1552
	ds_bpermute_b32 v134, v131, v60
	ds_bpermute_b32 v135, v131, v61
	ds_bpermute_b32 v146, v131, v62
	ds_bpermute_b32 v147, v131, v63
	ds_bpermute_b32 v156, v131, v56
	ds_bpermute_b32 v157, v131, v57
	ds_bpermute_b32 v162, v131, v58
	ds_bpermute_b32 v163, v131, v59
	s_waitcnt vmcnt(12)
	v_cndmask_b32_e64 v148, v148, 1.0, s[40:41]
	v_cndmask_b32_e64 v149, v149, 1.0, s[40:41]
	v_cndmask_b32_e64 v150, v150, 1.0, s[40:41]
	v_cndmask_b32_e64 v151, v151, 1.0, s[40:41]
	v_cndmask_b32_e64 v152, v152, 1.0, s[40:41]
	v_cndmask_b32_e64 v153, v153, 1.0, s[40:41]
	v_cndmask_b32_e64 v154, v154, 1.0, s[40:41]
	v_cndmask_b32_e64 v155, v155, 1.0, s[40:41]
	v_xor_b32_e32 v164, v130, v164
	v_cndmask_b32_e64 v164, v164, 0, s[40:41]
	v_xor_b32_e32 v165, v130, v165
	v_cndmask_b32_e64 v165, v165, 0, s[40:41]
	v_xor_b32_e32 v166, v130, v166
	v_cndmask_b32_e64 v166, v166, 0, s[40:41]
	v_xor_b32_e32 v167, v130, v167
	v_cndmask_b32_e64 v167, v167, 0, s[40:41]
	v_xor_b32_e32 v168, v130, v168
	v_cndmask_b32_e64 v168, v168, 0, s[40:41]
	v_xor_b32_e32 v169, v130, v169
	v_cndmask_b32_e64 v169, v169, 0, s[40:41]
	v_xor_b32_e32 v170, v130, v170
	v_cndmask_b32_e64 v170, v170, 0, s[40:41]
	v_xor_b32_e32 v171, v130, v171
	v_cndmask_b32_e64 v171, v171, 0, s[40:41]
	s_mul_i32 s4, s73, 8
	v_add_u32_e32 v132, s4, v128
	s_waitcnt lgkmcnt(0)
	v_mul_f32_e32 v134, v164, v134
	v_mul_f32_e32 v135, v165, v135
	v_mul_f32_e32 v146, v166, v146
	v_mul_f32_e32 v147, v167, v147
	v_mul_f32_e32 v156, v168, v156
	v_mul_f32_e32 v157, v169, v157
	v_mul_f32_e32 v162, v170, v162
	v_mul_f32_e32 v163, v171, v163
	v_fma_f32 v60, v60, v148, v134
	v_fma_f32 v61, v61, v149, v135
	v_fma_f32 v62, v62, v150, v146
	v_fma_f32 v63, v63, v151, v147
	v_fma_f32 v56, v56, v152, v156
	v_fma_f32 v57, v57, v153, v157
	v_fma_f32 v58, v58, v154, v162
	v_fma_f32 v59, v59, v155, v163
	ds_bpermute_b32 v134, v131, v52
	ds_bpermute_b32 v135, v131, v53
	ds_bpermute_b32 v146, v131, v54
	ds_bpermute_b32 v147, v131, v55
	ds_bpermute_b32 v156, v131, v48
	ds_bpermute_b32 v157, v131, v49
	ds_bpermute_b32 v162, v131, v50
	ds_bpermute_b32 v163, v131, v51
	v_cvt_pk_bf16_f32 v60, v60, v61
	v_cvt_pk_bf16_f32 v61, v62, v63
	v_cvt_pk_bf16_f32 v62, v56, v57
	v_cvt_pk_bf16_f32 v63, v58, v59
	global_store_dwordx4 v132, v[60:63], s[42:43] offset:0 sc1
	s_waitcnt lgkmcnt(0)
	v_mul_f32_e32 v134, v164, v134
	v_mul_f32_e32 v135, v165, v135
	v_mul_f32_e32 v146, v166, v146
	v_mul_f32_e32 v147, v167, v147
	v_mul_f32_e32 v156, v168, v156
	v_mul_f32_e32 v157, v169, v157
	v_mul_f32_e32 v162, v170, v162
	v_mul_f32_e32 v163, v171, v163
	v_fma_f32 v52, v52, v148, v134
	v_fma_f32 v53, v53, v149, v135
	v_fma_f32 v54, v54, v150, v146
	v_fma_f32 v55, v55, v151, v147
	v_fma_f32 v48, v48, v152, v156
	v_fma_f32 v49, v49, v153, v157
	v_fma_f32 v50, v50, v154, v162
	v_fma_f32 v51, v51, v155, v163
	v_cvt_pk_bf16_f32 v52, v52, v53
	v_cvt_pk_bf16_f32 v53, v54, v55
	v_cvt_pk_bf16_f32 v54, v48, v49
	v_cvt_pk_bf16_f32 v55, v50, v51
	global_store_dwordx4 v132, v[52:55], s[42:43] offset:256 sc1
	ds_bpermute_b32 v134, v131, v44
	ds_bpermute_b32 v135, v131, v45
	ds_bpermute_b32 v146, v131, v46
	ds_bpermute_b32 v147, v131, v47
	ds_bpermute_b32 v156, v131, v40
	ds_bpermute_b32 v157, v131, v41
	ds_bpermute_b32 v162, v131, v42
	ds_bpermute_b32 v163, v131, v43
	s_waitcnt vmcnt(10)
	v_cndmask_b32_e64 v172, v172, 1.0, s[40:41]
	v_cndmask_b32_e64 v173, v173, 1.0, s[40:41]
	v_cndmask_b32_e64 v174, v174, 1.0, s[40:41]
	v_cndmask_b32_e64 v175, v175, 1.0, s[40:41]
	v_cndmask_b32_e64 v176, v176, 1.0, s[40:41]
	v_cndmask_b32_e64 v177, v177, 1.0, s[40:41]
	v_cndmask_b32_e64 v178, v178, 1.0, s[40:41]
	v_cndmask_b32_e64 v179, v179, 1.0, s[40:41]
	v_xor_b32_e32 v180, v130, v180
	v_cndmask_b32_e64 v180, v180, 0, s[40:41]
	v_xor_b32_e32 v181, v130, v181
	v_cndmask_b32_e64 v181, v181, 0, s[40:41]
	v_xor_b32_e32 v182, v130, v182
	v_cndmask_b32_e64 v182, v182, 0, s[40:41]
	v_xor_b32_e32 v183, v130, v183
	v_cndmask_b32_e64 v183, v183, 0, s[40:41]
	v_xor_b32_e32 v184, v130, v184
	v_cndmask_b32_e64 v184, v184, 0, s[40:41]
	v_xor_b32_e32 v185, v130, v185
	v_cndmask_b32_e64 v185, v185, 0, s[40:41]
	v_xor_b32_e32 v186, v130, v186
	v_cndmask_b32_e64 v186, v186, 0, s[40:41]
	v_xor_b32_e32 v187, v130, v187
	v_cndmask_b32_e64 v187, v187, 0, s[40:41]
	s_mul_i32 s4, s73, 9
	v_add_u32_e32 v132, s4, v128
	s_waitcnt lgkmcnt(0)
	v_mul_f32_e32 v134, v180, v134
	v_mul_f32_e32 v135, v181, v135
	v_mul_f32_e32 v146, v182, v146
	v_mul_f32_e32 v147, v183, v147
	v_mul_f32_e32 v156, v184, v156
	v_mul_f32_e32 v157, v185, v157
	v_mul_f32_e32 v162, v186, v162
	v_mul_f32_e32 v163, v187, v163
	v_fma_f32 v44, v44, v172, v134
	v_fma_f32 v45, v45, v173, v135
	v_fma_f32 v46, v46, v174, v146
	v_fma_f32 v47, v47, v175, v147
	v_fma_f32 v40, v40, v176, v156
	v_fma_f32 v41, v41, v177, v157
	v_fma_f32 v42, v42, v178, v162
	v_fma_f32 v43, v43, v179, v163
	ds_bpermute_b32 v134, v131, v36
	ds_bpermute_b32 v135, v131, v37
	ds_bpermute_b32 v146, v131, v38
	ds_bpermute_b32 v147, v131, v39
	ds_bpermute_b32 v156, v131, v32
	ds_bpermute_b32 v157, v131, v33
	ds_bpermute_b32 v162, v131, v34
	ds_bpermute_b32 v163, v131, v35
	v_cvt_pk_bf16_f32 v44, v44, v45
	v_cvt_pk_bf16_f32 v45, v46, v47
	v_cvt_pk_bf16_f32 v46, v40, v41
	v_cvt_pk_bf16_f32 v47, v42, v43
	global_store_dwordx4 v132, v[44:47], s[42:43] offset:0 sc1
	s_waitcnt lgkmcnt(0)
	v_mul_f32_e32 v134, v180, v134
	v_mul_f32_e32 v135, v181, v135
	v_mul_f32_e32 v146, v182, v146
	v_mul_f32_e32 v147, v183, v147
	v_mul_f32_e32 v156, v184, v156
	v_mul_f32_e32 v157, v185, v157
	v_mul_f32_e32 v162, v186, v162
	v_mul_f32_e32 v163, v187, v163
	v_fma_f32 v36, v36, v172, v134
	v_fma_f32 v37, v37, v173, v135
	v_fma_f32 v38, v38, v174, v146
	v_fma_f32 v39, v39, v175, v147
	v_fma_f32 v32, v32, v176, v156
	v_fma_f32 v33, v33, v177, v157
	v_fma_f32 v34, v34, v178, v162
	v_fma_f32 v35, v35, v179, v163
	v_cvt_pk_bf16_f32 v36, v36, v37
	v_cvt_pk_bf16_f32 v37, v38, v39
	v_cvt_pk_bf16_f32 v38, v32, v33
	v_cvt_pk_bf16_f32 v39, v34, v35
	global_store_dwordx4 v132, v[36:39], s[42:43] offset:256 sc1
	ds_bpermute_b32 v134, v131, v28
	ds_bpermute_b32 v135, v131, v29
	ds_bpermute_b32 v146, v131, v30
	ds_bpermute_b32 v147, v131, v31
	ds_bpermute_b32 v156, v131, v24
	ds_bpermute_b32 v157, v131, v25
	ds_bpermute_b32 v162, v131, v26
	ds_bpermute_b32 v163, v131, v27
	s_waitcnt vmcnt(8)
	v_cndmask_b32_e64 v188, v188, 1.0, s[40:41]
	v_cndmask_b32_e64 v189, v189, 1.0, s[40:41]
	v_cndmask_b32_e64 v190, v190, 1.0, s[40:41]
	v_cndmask_b32_e64 v191, v191, 1.0, s[40:41]
	v_cndmask_b32_e64 v208, v208, 1.0, s[40:41]
	v_cndmask_b32_e64 v209, v209, 1.0, s[40:41]
	v_cndmask_b32_e64 v210, v210, 1.0, s[40:41]
	v_cndmask_b32_e64 v211, v211, 1.0, s[40:41]
	v_xor_b32_e32 v212, v130, v212
	v_cndmask_b32_e64 v212, v212, 0, s[40:41]
	v_xor_b32_e32 v213, v130, v213
	v_cndmask_b32_e64 v213, v213, 0, s[40:41]
	v_xor_b32_e32 v214, v130, v214
	v_cndmask_b32_e64 v214, v214, 0, s[40:41]
	v_xor_b32_e32 v215, v130, v215
	v_cndmask_b32_e64 v215, v215, 0, s[40:41]
	v_xor_b32_e32 v216, v130, v216
	v_cndmask_b32_e64 v216, v216, 0, s[40:41]
	v_xor_b32_e32 v217, v130, v217
	v_cndmask_b32_e64 v217, v217, 0, s[40:41]
	v_xor_b32_e32 v218, v130, v218
	v_cndmask_b32_e64 v218, v218, 0, s[40:41]
	v_xor_b32_e32 v219, v130, v219
	v_cndmask_b32_e64 v219, v219, 0, s[40:41]
	s_mul_i32 s4, s73, 10
	v_add_u32_e32 v132, s4, v128
	s_waitcnt lgkmcnt(0)
	v_mul_f32_e32 v134, v212, v134
	v_mul_f32_e32 v135, v213, v135
	v_mul_f32_e32 v146, v214, v146
	v_mul_f32_e32 v147, v215, v147
	v_mul_f32_e32 v156, v216, v156
	v_mul_f32_e32 v157, v217, v157
	v_mul_f32_e32 v162, v218, v162
	v_mul_f32_e32 v163, v219, v163
	v_fma_f32 v28, v28, v188, v134
	v_fma_f32 v29, v29, v189, v135
	v_fma_f32 v30, v30, v190, v146
	v_fma_f32 v31, v31, v191, v147
	v_fma_f32 v24, v24, v208, v156
	v_fma_f32 v25, v25, v209, v157
	v_fma_f32 v26, v26, v210, v162
	v_fma_f32 v27, v27, v211, v163
	ds_bpermute_b32 v134, v131, v20
	ds_bpermute_b32 v135, v131, v21
	ds_bpermute_b32 v146, v131, v22
	ds_bpermute_b32 v147, v131, v23
	ds_bpermute_b32 v156, v131, v16
	ds_bpermute_b32 v157, v131, v17
	ds_bpermute_b32 v162, v131, v18
	ds_bpermute_b32 v163, v131, v19
	v_cvt_pk_bf16_f32 v28, v28, v29
	v_cvt_pk_bf16_f32 v29, v30, v31
	v_cvt_pk_bf16_f32 v30, v24, v25
	v_cvt_pk_bf16_f32 v31, v26, v27
	global_store_dwordx4 v132, v[28:31], s[42:43] offset:0 sc1
	s_waitcnt lgkmcnt(0)
	v_mul_f32_e32 v134, v212, v134
	v_mul_f32_e32 v135, v213, v135
	v_mul_f32_e32 v146, v214, v146
	v_mul_f32_e32 v147, v215, v147
	v_mul_f32_e32 v156, v216, v156
	v_mul_f32_e32 v157, v217, v157
	v_mul_f32_e32 v162, v218, v162
	v_mul_f32_e32 v163, v219, v163
	v_fma_f32 v20, v20, v188, v134
	v_fma_f32 v21, v21, v189, v135
	v_fma_f32 v22, v22, v190, v146
	v_fma_f32 v23, v23, v191, v147
	v_fma_f32 v16, v16, v208, v156
	v_fma_f32 v17, v17, v209, v157
	v_fma_f32 v18, v18, v210, v162
	v_fma_f32 v19, v19, v211, v163
	v_cvt_pk_bf16_f32 v20, v20, v21
	v_cvt_pk_bf16_f32 v21, v22, v23
	v_cvt_pk_bf16_f32 v22, v16, v17
	v_cvt_pk_bf16_f32 v23, v18, v19
	global_store_dwordx4 v132, v[20:23], s[42:43] offset:256 sc1
	ds_bpermute_b32 v134, v131, v12
	ds_bpermute_b32 v135, v131, v13
	ds_bpermute_b32 v146, v131, v14
	ds_bpermute_b32 v147, v131, v15
	ds_bpermute_b32 v156, v131, v8
	ds_bpermute_b32 v157, v131, v9
	ds_bpermute_b32 v162, v131, v10
	ds_bpermute_b32 v163, v131, v11
	s_waitcnt vmcnt(6)
	v_cndmask_b32_e64 v220, v220, 1.0, s[40:41]
	v_cndmask_b32_e64 v221, v221, 1.0, s[40:41]
	v_cndmask_b32_e64 v222, v222, 1.0, s[40:41]
	v_cndmask_b32_e64 v223, v223, 1.0, s[40:41]
	v_cndmask_b32_e64 v224, v224, 1.0, s[40:41]
	v_cndmask_b32_e64 v225, v225, 1.0, s[40:41]
	v_cndmask_b32_e64 v226, v226, 1.0, s[40:41]
	v_cndmask_b32_e64 v227, v227, 1.0, s[40:41]
	v_xor_b32_e32 v228, v130, v228
	v_cndmask_b32_e64 v228, v228, 0, s[40:41]
	v_xor_b32_e32 v229, v130, v229
	v_cndmask_b32_e64 v229, v229, 0, s[40:41]
	v_xor_b32_e32 v230, v130, v230
	v_cndmask_b32_e64 v230, v230, 0, s[40:41]
	v_xor_b32_e32 v231, v130, v231
	v_cndmask_b32_e64 v231, v231, 0, s[40:41]
	v_xor_b32_e32 v232, v130, v232
	v_cndmask_b32_e64 v232, v232, 0, s[40:41]
	v_xor_b32_e32 v233, v130, v233
	v_cndmask_b32_e64 v233, v233, 0, s[40:41]
	v_xor_b32_e32 v234, v130, v234
	v_cndmask_b32_e64 v234, v234, 0, s[40:41]
	v_xor_b32_e32 v235, v130, v235
	v_cndmask_b32_e64 v235, v235, 0, s[40:41]
	s_mul_i32 s4, s73, 11
	v_add_u32_e32 v132, s4, v128
	s_waitcnt lgkmcnt(0)
	v_mul_f32_e32 v134, v228, v134
	v_mul_f32_e32 v135, v229, v135
	v_mul_f32_e32 v146, v230, v146
	v_mul_f32_e32 v147, v231, v147
	v_mul_f32_e32 v156, v232, v156
	v_mul_f32_e32 v157, v233, v157
	v_mul_f32_e32 v162, v234, v162
	v_mul_f32_e32 v163, v235, v163
	v_fma_f32 v12, v12, v220, v134
	v_fma_f32 v13, v13, v221, v135
	v_fma_f32 v14, v14, v222, v146
	v_fma_f32 v15, v15, v223, v147
	v_fma_f32 v8, v8, v224, v156
	v_fma_f32 v9, v9, v225, v157
	v_fma_f32 v10, v10, v226, v162
	v_fma_f32 v11, v11, v227, v163
	ds_bpermute_b32 v134, v131, v4
	ds_bpermute_b32 v135, v131, v5
	ds_bpermute_b32 v146, v131, v6
	ds_bpermute_b32 v147, v131, v7
	ds_bpermute_b32 v156, v131, v0
	ds_bpermute_b32 v157, v131, v1
	ds_bpermute_b32 v162, v131, v2
	ds_bpermute_b32 v163, v131, v3
	v_cvt_pk_bf16_f32 v12, v12, v13
	v_cvt_pk_bf16_f32 v13, v14, v15
	v_cvt_pk_bf16_f32 v14, v8, v9
	v_cvt_pk_bf16_f32 v15, v10, v11
	global_store_dwordx4 v132, v[12:15], s[42:43] offset:0 sc1
	s_waitcnt lgkmcnt(0)
	v_mul_f32_e32 v134, v228, v134
	v_mul_f32_e32 v135, v229, v135
	v_mul_f32_e32 v146, v230, v146
	v_mul_f32_e32 v147, v231, v147
	v_mul_f32_e32 v156, v232, v156
	v_mul_f32_e32 v157, v233, v157
	v_mul_f32_e32 v162, v234, v162
	v_mul_f32_e32 v163, v235, v163
	v_fma_f32 v4, v4, v220, v134
	v_fma_f32 v5, v5, v221, v135
	v_fma_f32 v6, v6, v222, v146
	v_fma_f32 v7, v7, v223, v147
	v_fma_f32 v0, v0, v224, v156
	v_fma_f32 v1, v1, v225, v157
	v_fma_f32 v2, v2, v226, v162
	v_fma_f32 v3, v3, v227, v163
	v_cvt_pk_bf16_f32 v4, v4, v5
	v_cvt_pk_bf16_f32 v5, v6, v7
	v_cvt_pk_bf16_f32 v6, v0, v1
	v_cvt_pk_bf16_f32 v7, v2, v3
	global_store_dwordx4 v132, v[4:7], s[42:43] offset:256 sc1

.LBB0_568:
	v_cvt_pk_bf16_f32 v4, v4, v5
	v_cvt_pk_bf16_f32 v5, v6, v7
	v_cvt_pk_bf16_f32 v6, v0, v1
	v_cvt_pk_bf16_f32 v7, v2, v3
	s_andn2_b64 vcc, exec, s[36:37]
	s_mov_b64 s[4:5], -1
	global_store_dwordx4 v[128:129], v[4:7], off offset:256 sc1
